# GEMM K loop: stage DMAs one MFMA later (behind MFMA 6,9,12,15,20,26)
# baseline (speedup 1.0000x reference)
.LBB0_246:
	s_add_i32 s10, s7, 0xffffa000
	s_cmp_lg_u32 s7, 0
	s_cselect_b32 s12, s10, 0xc000
	v_add_u32_e32 v131, s7, v150
	s_waitcnt vmcnt(6)
	s_barrier
	v_add_u32_e32 v133, s7, v149
	ds_read_b128 v[154:157], v131 offset:0
	ds_read_b128 v[158:161], v131 offset:0x400
	ds_read_b128 v[162:165], v131 offset:0x800
	ds_read_b128 v[166:169], v131 offset:0xc00
	v_add_u32_e32 v131, s12, v147
	ds_read_b128 v[170:173], v133 offset:0
	ds_read_b128 v[174:177], v133 offset:0x400
	ds_read_b128 v[178:181], v133 offset:0x800
	ds_read_b128 v[200:203], v133 offset:0xc00
	ds_read_b128 v[204:207], v133 offset:0x1000
	ds_read_b128 v[208:211], v133 offset:0x1400
	ds_read_b128 v[212:215], v133 offset:0x1800
	ds_read_b128 v[216:219], v133 offset:0x1c00
	s_add_u32 s10, s8, s50
	s_addc_u32 s11, s9, s51
	v_readfirstlane_b32 s13, v131
	s_add_u32 s64, s5, s100
	s_addc_u32 s65, s6, 0
	s_add_i32 s66, s7, 0x6000
	s_cmpk_lg_u32 s7, 0xc000
	s_cselect_b32 s7, s66, 0
	s_addk_i32 s100, 0x400
	s_add_u32 s50, s50, s60
	s_addc_u32 s51, s51, 0
	s_sub_i32 s68, s13, s12
	s_lshr_b32 s68, s68, 1
	s_add_i32 s68, s68, s12
	s_addk_i32 s68, 0x4000
	s_waitcnt lgkmcnt(4)
	v_mfma_f32_16x16x32_bf16 v[126:129], v[154:157], v[170:173], v[126:129]
	v_mfma_f32_16x16x32_bf16 v[122:125], v[154:157], v[174:177], v[122:125]
	v_mfma_f32_16x16x32_bf16 v[118:121], v[154:157], v[178:181], v[118:121]
	v_mfma_f32_16x16x32_bf16 v[114:117], v[154:157], v[200:203], v[114:117]
	v_mfma_f32_16x16x32_bf16 v[110:113], v[158:161], v[170:173], v[110:113]
	s_mov_b32 m0, s13
	v_mfma_f32_16x16x32_bf16 v[102:105], v[158:161], v[174:177], v[102:105]
	global_load_lds_dwordx4 v0, s[10:11]
	v_mfma_f32_16x16x32_bf16 v[94:97], v[158:161], v[178:181], v[94:97]
	v_mfma_f32_16x16x32_bf16 v[86:89], v[158:161], v[200:203], v[86:89]
	s_add_u32 m0, s13, 0x400
	v_mfma_f32_16x16x32_bf16 v[78:81], v[162:165], v[170:173], v[78:81]
	global_load_lds_dwordx4 v130, s[10:11]
	v_mfma_f32_16x16x32_bf16 v[70:73], v[162:165], v[174:177], v[70:73]
	v_mfma_f32_16x16x32_bf16 v[62:65], v[162:165], v[178:181], v[62:65]
	s_add_u32 m0, s13, 0x800
	v_mfma_f32_16x16x32_bf16 v[54:57], v[162:165], v[200:203], v[54:57]
	global_load_lds_dwordx4 v132, s[10:11]
	v_mfma_f32_16x16x32_bf16 v[46:49], v[166:169], v[170:173], v[46:49]
	v_mfma_f32_16x16x32_bf16 v[38:41], v[166:169], v[174:177], v[38:41]
	s_add_u32 m0, s13, 0xc00
	v_mfma_f32_16x16x32_bf16 v[30:33], v[166:169], v[178:181], v[30:33]
	global_load_lds_dwordx4 v136, s[10:11]
	v_mfma_f32_16x16x32_bf16 v[22:25], v[166:169], v[200:203], v[22:25]
	s_waitcnt lgkmcnt(0)
	v_mfma_f32_16x16x32_bf16 v[106:109], v[154:157], v[204:207], v[106:109]
	v_mfma_f32_16x16x32_bf16 v[98:101], v[154:157], v[208:211], v[98:101]
	v_mfma_f32_16x16x32_bf16 v[90:93], v[154:157], v[212:215], v[90:93]
	s_mov_b32 m0, s68
	v_mfma_f32_16x16x32_bf16 v[82:85], v[154:157], v[216:219], v[82:85]
	global_load_lds_dwordx4 v138, s[64:65]
	v_mfma_f32_16x16x32_bf16 v[74:77], v[158:161], v[204:207], v[74:77]
	v_mfma_f32_16x16x32_bf16 v[66:69], v[158:161], v[208:211], v[66:69]
	v_mfma_f32_16x16x32_bf16 v[58:61], v[158:161], v[212:215], v[58:61]
	v_mfma_f32_16x16x32_bf16 v[50:53], v[158:161], v[216:219], v[50:53]
	v_mfma_f32_16x16x32_bf16 v[42:45], v[162:165], v[204:207], v[42:45]
	s_add_u32 m0, s68, 0x400
	v_mfma_f32_16x16x32_bf16 v[34:37], v[162:165], v[208:211], v[34:37]
	global_load_lds_dwordx4 v140, s[64:65]
	v_mfma_f32_16x16x32_bf16 v[26:29], v[162:165], v[212:215], v[26:29]
	v_mfma_f32_16x16x32_bf16 v[18:21], v[162:165], v[216:219], v[18:21]
	v_mfma_f32_16x16x32_bf16 v[14:17], v[166:169], v[204:207], v[14:17]
	v_mfma_f32_16x16x32_bf16 v[10:13], v[166:169], v[208:211], v[10:13]
	v_mfma_f32_16x16x32_bf16 v[6:9], v[166:169], v[212:215], v[6:9]
	v_mfma_f32_16x16x32_bf16 v[2:5], v[166:169], v[216:219], v[2:5]
	s_cmpk_lg_i32 s100, 0x7800
	s_cbranch_scc1 .LBB0_246
	s_waitcnt vmcnt(6)
	s_barrier
	v_add_u32_e32 v0, s7, v150
	v_add_u32_e32 v140, s7, v149
	ds_read_b128 v[130:133], v0 offset:0
	ds_read_b128 v[136:139], v0 offset:0x400
	ds_read_b128 v[154:157], v0 offset:0x800
	ds_read_b128 v[158:161], v0 offset:0xc00
	ds_read_b128 v[162:165], v140 offset:0
	ds_read_b128 v[166:169], v140 offset:0x400
	ds_read_b128 v[170:173], v140 offset:0x800
	ds_read_b128 v[174:177], v140 offset:0xc00
	ds_read_b128 v[178:181], v140 offset:0x1000
	ds_read_b128 v[200:203], v140 offset:0x1400
	ds_read_b128 v[204:207], v140 offset:0x1800
	ds_read_b128 v[208:211], v140 offset:0x1c00
	s_lshl_b32 s49, s4, 8
	s_waitcnt lgkmcnt(4)
	s_nop 0
	v_mfma_f32_16x16x32_bf16 v[126:129], v[130:133], v[162:165], v[126:129]
	v_mfma_f32_16x16x32_bf16 v[118:121], v[130:133], v[170:173], v[118:121]
	v_mfma_f32_16x16x32_bf16 v[114:117], v[130:133], v[174:177], v[114:117]
	v_mfma_f32_16x16x32_bf16 v[110:113], v[136:139], v[162:165], v[110:113]
	v_mfma_f32_16x16x32_bf16 v[102:105], v[136:139], v[166:169], v[102:105]
	v_mfma_f32_16x16x32_bf16 v[94:97], v[136:139], v[170:173], v[94:97]
	v_mfma_f32_16x16x32_bf16 v[86:89], v[136:139], v[174:177], v[86:89]
	v_mfma_f32_16x16x32_bf16 v[70:73], v[154:157], v[166:169], v[70:73]
	v_mfma_f32_16x16x32_bf16 v[62:65], v[154:157], v[170:173], v[62:65]
	v_mfma_f32_16x16x32_bf16 v[54:57], v[154:157], v[174:177], v[54:57]
	v_mfma_f32_16x16x32_bf16 v[46:49], v[158:161], v[162:165], v[46:49]
	v_mfma_f32_16x16x32_bf16 v[38:41], v[158:161], v[166:169], v[38:41]
	v_mfma_f32_16x16x32_bf16 v[30:33], v[158:161], v[170:173], v[30:33]
	v_mfma_f32_16x16x32_bf16 v[22:25], v[158:161], v[174:177], v[22:25]
	v_mfma_f32_16x16x32_bf16 v[212:215], v[130:133], v[166:169], v[122:125]
	v_mfma_f32_16x16x32_bf16 v[216:219], v[154:157], v[162:165], v[78:81]
	s_waitcnt lgkmcnt(0)
	s_nop 0
	v_mfma_f32_16x16x32_bf16 v[174:177], v[136:139], v[178:181], v[74:77]
	v_mfma_f32_16x16x32_bf16 v[220:223], v[136:139], v[200:203], v[66:69]
	v_mfma_f32_16x16x32_bf16 v[224:227], v[136:139], v[204:207], v[58:61]
	v_mfma_f32_16x16x32_bf16 v[50:53], v[136:139], v[208:211], v[50:53]
	v_mfma_f32_16x16x32_bf16 v[136:139], v[154:157], v[178:181], v[42:45]
	v_mfma_f32_16x16x32_bf16 v[34:37], v[154:157], v[200:203], v[34:37]
	v_mfma_f32_16x16x32_bf16 v[6:9], v[158:161], v[204:207], v[6:9]
	v_mfma_f32_16x16x32_bf16 v[162:165], v[130:133], v[178:181], v[106:109]
	v_mfma_f32_16x16x32_bf16 v[166:169], v[130:133], v[200:203], v[98:101]
	v_mfma_f32_16x16x32_bf16 v[170:173], v[130:133], v[204:207], v[90:93]
	v_mfma_f32_16x16x32_bf16 v[130:133], v[130:133], v[208:211], v[82:85]
	v_mfma_f32_16x16x32_bf16 v[228:231], v[154:157], v[204:207], v[26:29]
	v_mfma_f32_16x16x32_bf16 v[154:157], v[154:157], v[208:211], v[18:21]
	v_mfma_f32_16x16x32_bf16 v[178:181], v[158:161], v[178:181], v[14:17]
	v_mfma_f32_16x16x32_bf16 v[200:203], v[158:161], v[200:203], v[10:13]
	v_mfma_f32_16x16x32_bf16 v[158:161], v[158:161], v[208:211], v[2:5]
	s_waitcnt vmcnt(0)
	s_barrier
	ds_read_b128 v[2:5], v151 offset:0
	ds_read_b128 v[14:17], v151 offset:0x400
	ds_read_b128 v[204:207], v151 offset:0x800
	ds_read_b128 v[208:211], v151 offset:0xc00
	ds_read_b128 v[10:13], v152 offset:0
	ds_read_b128 v[18:21], v152 offset:0x400
	ds_read_b128 v[26:29], v152 offset:0x800
	ds_read_b128 v[42:45], v152 offset:0xc00
	ds_read_b128 v[232:235], v152 offset:0x1000
	ds_read_b128 v[236:239], v152 offset:0x1400
	ds_read_b128 v[240:243], v152 offset:0x1800
	ds_read_b128 v[244:247], v152 offset:0x1c00
	s_nop 0
	s_waitcnt lgkmcnt(4)
	s_nop 0
	v_mfma_f32_16x16x32_bf16 v[122:125], v[2:5], v[10:13], v[126:129]
	v_mfma_f32_16x16x32_bf16 v[106:109], v[2:5], v[18:21], v[212:215]
	v_mfma_f32_16x16x32_bf16 v[90:93], v[2:5], v[26:29], v[118:121]
	v_mfma_f32_16x16x32_bf16 v[74:77], v[2:5], v[42:45], v[114:117]
	v_mfma_f32_16x16x32_bf16 v[126:129], v[14:17], v[10:13], v[110:113]
	v_mfma_f32_16x16x32_bf16 v[110:113], v[14:17], v[18:21], v[102:105]
	v_mfma_f32_16x16x32_bf16 v[94:97], v[14:17], v[26:29], v[94:97]
	v_mfma_f32_16x16x32_bf16 v[78:81], v[14:17], v[42:45], v[86:89]
	v_mfma_f32_16x16x32_bf16 v[114:117], v[204:207], v[10:13], v[216:219]
	v_mfma_f32_16x16x32_bf16 v[98:101], v[204:207], v[18:21], v[70:73]
	v_mfma_f32_16x16x32_bf16 v[82:85], v[204:207], v[26:29], v[62:65]
	v_mfma_f32_16x16x32_bf16 v[66:69], v[204:207], v[42:45], v[54:57]
	v_mfma_f32_16x16x32_bf16 v[118:121], v[208:211], v[10:13], v[46:49]
	v_mfma_f32_16x16x32_bf16 v[102:105], v[208:211], v[18:21], v[38:41]
	v_mfma_f32_16x16x32_bf16 v[86:89], v[208:211], v[26:29], v[30:33]
	v_mfma_f32_16x16x32_bf16 v[70:73], v[208:211], v[42:45], v[22:25]
	s_waitcnt lgkmcnt(0)
	s_nop 0
	v_mfma_f32_16x16x32_bf16 v[58:61], v[2:5], v[232:235], v[162:165]
	v_mfma_f32_16x16x32_bf16 v[42:45], v[2:5], v[236:239], v[166:169]
	v_mfma_f32_16x16x32_bf16 v[26:29], v[2:5], v[240:243], v[170:173]
	v_mfma_f32_16x16x32_bf16 v[10:13], v[2:5], v[244:247], v[130:133]
	v_mfma_f32_16x16x32_bf16 v[62:65], v[14:17], v[232:235], v[174:177]
	v_mfma_f32_16x16x32_bf16 v[46:49], v[14:17], v[236:239], v[220:223]
	v_mfma_f32_16x16x32_bf16 v[30:33], v[14:17], v[240:243], v[224:227]
	v_mfma_f32_16x16x32_bf16 v[14:17], v[14:17], v[244:247], v[50:53]
	v_mfma_f32_16x16x32_bf16 v[50:53], v[204:207], v[232:235], v[136:139]
	v_mfma_f32_16x16x32_bf16 v[34:37], v[204:207], v[236:239], v[34:37]
	v_mfma_f32_16x16x32_bf16 v[18:21], v[204:207], v[240:243], v[228:231]
	v_mfma_f32_16x16x32_bf16 v[2:5], v[204:207], v[244:247], v[154:157]
	v_mfma_f32_16x16x32_bf16 v[54:57], v[208:211], v[232:235], v[178:181]
	v_mfma_f32_16x16x32_bf16 v[38:41], v[208:211], v[236:239], v[200:203]
	v_mfma_f32_16x16x32_bf16 v[22:25], v[208:211], v[240:243], v[6:9]
	v_mfma_f32_16x16x32_bf16 v[6:9], v[208:211], v[244:247], v[158:161]
	v_mov_b32_e32 v136, v134
	s_mov_b64 s[50:51], -1
	s_and_b64 vcc, exec, s[22:23]
	s_barrier
	s_cbranch_vccz .LBB0_264
	s_and_b64 vcc, exec, s[0:1]
	s_cbranch_vccz .LBB0_250
	v_lshrrev_b32_e32 v0, 6, v136
	v_mul_lo_u32 v137, v0, s14
	v_and_b32_e32 v130, 15, v136
	v_and_or_b32 v0, v136, 48, v137
	s_movk_i32 s4, 0x90
	v_mad_u32_u24 v0, v130, s4, v0
	v_cvt_pk_bf16_f32 v130, v122, v123
	v_cvt_pk_bf16_f32 v131, v124, v125
	v_cvt_pk_bf16_f32 v132, v126, v127
	v_cvt_pk_bf16_f32 v133, v128, v129
	s_waitcnt vmcnt(0)
	ds_write_b128 v0, v[130:133]
	v_cvt_pk_bf16_f32 v130, v114, v115
	v_cvt_pk_bf16_f32 v131, v116, v117
	v_cvt_pk_bf16_f32 v132, v118, v119
	v_cvt_pk_bf16_f32 v133, v120, v121
	ds_write_b128 v0, v[130:133] offset:64
	v_cvt_pk_bf16_f32 v130, v106, v107
	v_cvt_pk_bf16_f32 v131, v108, v109
	v_cvt_pk_bf16_f32 v132, v110, v111
	v_cvt_pk_bf16_f32 v133, v112, v113
	ds_write_b128 v0, v[130:133] offset:2304
	v_cvt_pk_bf16_f32 v130, v98, v99
	v_cvt_pk_bf16_f32 v131, v100, v101
	v_cvt_pk_bf16_f32 v132, v102, v103
	v_cvt_pk_bf16_f32 v133, v104, v105
	ds_write_b128 v0, v[130:133] offset:2368
	v_cvt_pk_bf16_f32 v130, v90, v91
	v_cvt_pk_bf16_f32 v131, v92, v93
	v_cvt_pk_bf16_f32 v132, v94, v95
	v_cvt_pk_bf16_f32 v133, v96, v97
	ds_write_b128 v0, v[130:133] offset:4608
	v_cvt_pk_bf16_f32 v130, v82, v83
	v_cvt_pk_bf16_f32 v131, v84, v85
	v_cvt_pk_bf16_f32 v132, v86, v87
	v_cvt_pk_bf16_f32 v133, v88, v89
	ds_write_b128 v0, v[130:133] offset:4672
	v_cvt_pk_bf16_f32 v130, v74, v75
	v_cvt_pk_bf16_f32 v131, v76, v77
	v_cvt_pk_bf16_f32 v132, v78, v79
	v_cvt_pk_bf16_f32 v133, v80, v81
	ds_write_b128 v0, v[130:133] offset:6912
	v_cvt_pk_bf16_f32 v130, v66, v67
	v_cvt_pk_bf16_f32 v131, v68, v69
	v_cvt_pk_bf16_f32 v132, v70, v71
	v_cvt_pk_bf16_f32 v133, v72, v73
	ds_write_b128 v0, v[130:133] offset:6976
	v_cvt_pk_bf16_f32 v130, v58, v59
	v_cvt_pk_bf16_f32 v131, v60, v61
	v_cvt_pk_bf16_f32 v132, v62, v63
	v_cvt_pk_bf16_f32 v133, v64, v65
	ds_write_b128 v0, v[130:133] offset:9216
	v_cvt_pk_bf16_f32 v130, v50, v51
	v_cvt_pk_bf16_f32 v131, v52, v53
	v_cvt_pk_bf16_f32 v132, v54, v55
	v_cvt_pk_bf16_f32 v133, v56, v57
	ds_write_b128 v0, v[130:133] offset:9280
	v_cvt_pk_bf16_f32 v130, v42, v43
	v_cvt_pk_bf16_f32 v131, v44, v45
	v_cvt_pk_bf16_f32 v132, v46, v47
	v_cvt_pk_bf16_f32 v133, v48, v49
	ds_write_b128 v0, v[130:133] offset:11520
	v_cvt_pk_bf16_f32 v130, v34, v35
	v_cvt_pk_bf16_f32 v131, v36, v37
	v_cvt_pk_bf16_f32 v132, v38, v39
	v_cvt_pk_bf16_f32 v133, v40, v41
	ds_write_b128 v0, v[130:133] offset:11584
	v_cvt_pk_bf16_f32 v130, v26, v27
	v_cvt_pk_bf16_f32 v131, v28, v29
	v_cvt_pk_bf16_f32 v132, v30, v31
	v_cvt_pk_bf16_f32 v133, v32, v33
	ds_write_b128 v0, v[130:133] offset:13824
	v_cvt_pk_bf16_f32 v130, v18, v19
	v_cvt_pk_bf16_f32 v131, v20, v21
	v_cvt_pk_bf16_f32 v132, v22, v23
	v_cvt_pk_bf16_f32 v133, v24, v25
	ds_write_b128 v0, v[130:133] offset:13888
	v_cvt_pk_bf16_f32 v130, v10, v11
	v_cvt_pk_bf16_f32 v131, v12, v13
	v_cvt_pk_bf16_f32 v132, v14, v15
	v_cvt_pk_bf16_f32 v133, v16, v17
	ds_write_b128 v0, v[130:133] offset:16128
	v_cvt_pk_bf16_f32 v130, v2, v3
	v_cvt_pk_bf16_f32 v131, v4, v5
	v_cvt_pk_bf16_f32 v132, v6, v7
	v_cvt_pk_bf16_f32 v133, v8, v9
	ds_write_b128 v0, v[130:133] offset:16192
	v_and_b32_e32 v0, 0xffffff80, v136
	v_add_u32_e32 v130, s48, v0
	v_ashrrev_i32_e32 v131, 31, v130
	v_lshlrev_b64 v[130:131], 11, v[130:131]
	v_lshl_add_u64 v[130:131], s[38:39], 0, v[130:131]
	v_and_b32_e32 v0, 64, v136
	v_lshl_add_u64 v[130:131], s[46:47], 1, v[130:131]
	v_lshlrev_b32_e32 v0, 1, v0
	v_lshl_add_u64 v[138:139], v[130:131], 0, v[0:1]
	v_lshlrev_b32_e32 v0, 4, v136
	v_and_b32_e32 v0, 0x70, v0
	v_bfe_u32 v140, v136, 3, 3
	v_or_b32_e32 v130, v137, v0
	s_waitcnt lgkmcnt(0)
	v_mad_u32_u24 v137, v140, s4, v130
	ds_read_b128 v[66:69], v137
	ds_read_b128 v[70:73], v137 offset:1152
	ds_read_b128 v[74:77], v137 offset:2304
	ds_read_b128 v[78:81], v137 offset:3456
	ds_read_b128 v[82:85], v137 offset:4608
	ds_read_b128 v[86:89], v137 offset:5760
	ds_read_b128 v[90:93], v137 offset:6912
	ds_read_b128 v[94:97], v137 offset:8064
	ds_read_b128 v[98:101], v137 offset:9216
	ds_read_b128 v[102:105], v137 offset:10368
	ds_read_b128 v[106:109], v137 offset:11520
	ds_read_b128 v[110:113], v137 offset:12672
	ds_read_b128 v[114:117], v137 offset:13824
	ds_read_b128 v[118:121], v137 offset:14976
	ds_read_b128 v[122:125], v137 offset:16128
	ds_read_b128 v[126:129], v137 offset:17280
	v_lshl_add_u64 v[138:139], v[138:139], 0, v[0:1]
	v_lshlrev_b32_e32 v0, 11, v140
	v_lshl_add_u64 v[140:141], v[138:139], 0, v[0:1]
	s_mov_b64 s[50:51], 0
	s_waitcnt lgkmcnt(15)
	global_store_dwordx4 v[140:141], v[66:69], off
	v_or_b32_e32 v140, 0x4000, v0
	v_mov_b32_e32 v141, v1
	v_lshl_add_u64 v[140:141], v[138:139], 0, v[140:141]
	s_waitcnt lgkmcnt(14)
	global_store_dwordx4 v[140:141], v[70:73], off
	v_or_b32_e32 v140, 0x8000, v0
	v_mov_b32_e32 v141, v1
	v_lshl_add_u64 v[140:141], v[138:139], 0, v[140:141]
	s_waitcnt lgkmcnt(13)
	global_store_dwordx4 v[140:141], v[74:77], off
	v_or_b32_e32 v140, 0xc000, v0
	v_mov_b32_e32 v141, v1
	v_lshl_add_u64 v[140:141], v[138:139], 0, v[140:141]
	s_waitcnt lgkmcnt(12)
	global_store_dwordx4 v[140:141], v[78:81], off
	v_or_b32_e32 v140, 0x10000, v0
	v_mov_b32_e32 v141, v1
	v_lshl_add_u64 v[140:141], v[138:139], 0, v[140:141]
	s_waitcnt lgkmcnt(11)
	global_store_dwordx4 v[140:141], v[82:85], off
	v_or_b32_e32 v140, 0x14000, v0
	v_mov_b32_e32 v141, v1
	v_lshl_add_u64 v[140:141], v[138:139], 0, v[140:141]
	s_waitcnt lgkmcnt(10)
	global_store_dwordx4 v[140:141], v[86:89], off
	v_or_b32_e32 v140, 0x18000, v0
	v_mov_b32_e32 v141, v1
	v_lshl_add_u64 v[140:141], v[138:139], 0, v[140:141]
	s_waitcnt lgkmcnt(9)
	global_store_dwordx4 v[140:141], v[90:93], off
	v_or_b32_e32 v140, 0x1c000, v0
	v_mov_b32_e32 v141, v1
	v_lshl_add_u64 v[140:141], v[138:139], 0, v[140:141]
	s_waitcnt lgkmcnt(8)
	global_store_dwordx4 v[140:141], v[94:97], off
	v_or_b32_e32 v140, 0x20000, v0
	v_mov_b32_e32 v141, v1
	v_lshl_add_u64 v[140:141], v[138:139], 0, v[140:141]
	s_waitcnt lgkmcnt(7)
	global_store_dwordx4 v[140:141], v[98:101], off
	v_or_b32_e32 v140, 0x24000, v0
	v_mov_b32_e32 v141, v1
	v_lshl_add_u64 v[140:141], v[138:139], 0, v[140:141]
	s_waitcnt lgkmcnt(6)
	global_store_dwordx4 v[140:141], v[102:105], off
	v_or_b32_e32 v140, 0x28000, v0
	v_mov_b32_e32 v141, v1
	v_lshl_add_u64 v[140:141], v[138:139], 0, v[140:141]
	s_waitcnt lgkmcnt(5)
	global_store_dwordx4 v[140:141], v[106:109], off
	v_or_b32_e32 v140, 0x2c000, v0
	v_mov_b32_e32 v141, v1
	v_lshl_add_u64 v[140:141], v[138:139], 0, v[140:141]
	s_waitcnt lgkmcnt(4)
	global_store_dwordx4 v[140:141], v[110:113], off
	v_or_b32_e32 v140, 0x30000, v0
	v_mov_b32_e32 v141, v1
	v_lshl_add_u64 v[140:141], v[138:139], 0, v[140:141]
	s_waitcnt lgkmcnt(3)
	global_store_dwordx4 v[140:141], v[114:117], off
	v_or_b32_e32 v140, 0x34000, v0
	v_mov_b32_e32 v141, v1
	v_lshl_add_u64 v[140:141], v[138:139], 0, v[140:141]
	s_waitcnt lgkmcnt(2)
	global_store_dwordx4 v[140:141], v[118:121], off
	v_or_b32_e32 v140, 0x38000, v0
	v_mov_b32_e32 v141, v1
	v_lshl_add_u64 v[140:141], v[138:139], 0, v[140:141]
	v_or_b32_e32 v0, 0x3c000, v0
	s_waitcnt lgkmcnt(1)
	global_store_dwordx4 v[140:141], v[122:125], off
	v_lshl_add_u64 v[138:139], v[138:139], 0, v[0:1]
	s_waitcnt lgkmcnt(0)
	global_store_dwordx4 v[138:139], v[126:129], off
	s_waitcnt lgkmcnt(0)
	s_barrier
